# scan of the gated-deltanet jobs hand-written (MFMA recurrence with scalar bases, immediate offsets, in-place accumulators); both scan loops now hand-written
# speedup vs baseline: 1.0132x; 1.0132x over previous
; __device__ __forceinline__ float bf_lo(unsigned u) { return __uint_as_float(u << 16); }
; __device__ __forceinline__ float bf_hi(unsigned u) { return __uint_as_float(u & 0xffff0000u); }
; __device__ __forceinline__ unsigned pk2(float lo, float hi) { return pg8::cvt_pk_bf16(lo, hi); }
; __device__ __forceinline__ void scan_phase(const Ctx& X, int wave, int lane) {
;     ...
;     if (mixer == 1) {
;         const bf16_t* mm0 = WSP(const bf16_t, WS_MM) + (size_t)(uid0 - 2048) * 4096;
;         u32x2 cb[4][4], ca[4][4][2][2];
;     ...
;         SCAN_LOAD_G(0, 0) SCAN_LOAD_G(1, 1) SCAN_LOAD_G(2, 2)
; #pragma unroll 1
;         for (int c0 = 0; c0 < NCH; c0 += 4) {
; #pragma unroll
;             for (int k = 0; k < 4; ++k) {
;                 const int c = c0 + k;
;                 SCAN_LOAD_G((k + 3) & 3, c + 3)
;                 bf16_t* bcc = bc0 + (size_t)c * 4096;
;                 u32x2 sp[4];
; #pragma unroll
;                 for (int t = 0; t < 4; ++t) { sp[t].x = pk2(S[t][0], S[t][1]); sp[t].y = pk2(S[t][2], S[t][3]);
;                     asm volatile("" : "+v"(sp[t].x) : "v"(cb[k][t].x));
;                     *(u32x2*)(bcc + 256 * t) = sp[t]; }
;                 bf16x8 bfr[2];
; #pragma unroll
;                 for (int s2 = 0; s2 < 2; ++s2) { u32x4 w; w.x = sp[2 * s2].x; w.y = sp[2 * s2].y; w.z = sp[2 * s2 + 1].x; w.w = sp[2 * s2 + 1].y; bfr[s2] = __builtin_bit_cast(bf16x8, w); }
; #pragma unroll
;                 for (int t = 0; t < 4; ++t) {
;                     f32x4 acc = (f32x4){bf_lo(cb[k][t].x), bf_hi(cb[k][t].x), bf_lo(cb[k][t].y), bf_hi(cb[k][t].y)};
; #pragma unroll
;                     for (int s2 = 0; s2 < 2; ++s2) { u32x4 w; w.x = ca[k][t][s2][0].x; w.y = ca[k][t][s2][0].y; w.z = ca[k][t][s2][1].x; w.w = ca[k][t][s2][1].y;
;                         acc = __builtin_amdgcn_mfma_f32_16x16x32_bf16(__builtin_bit_cast(bf16x8, w), bfr[s2], acc, 0, 0, 0); }
;                     S[t][0] = acc[0]; S[t][1] = acc[1]; S[t][2] = acc[2]; S[t][3] = acc[3];
;                 }
;             }
;         }
.LBB0_736:
	s_and_b64 vcc, exec, s[0:1]
	s_cbranch_vccz .LBB0_739
	s_and_b32 s20, s2, 63
	s_lshr_b32 s21, s20, 2
	s_and_b32 s20, s20, 3
	s_add_i32 s25, s21, 16
	s_lshl_b32 s25, s25, 20
	s_lshl_b32 s20, s20, 11
	s_add_u32 s44, s30, 0x3500000
	s_addc_u32 s45, s31, 0
	s_add_u32 s44, s44, s25
	s_addc_u32 s45, s45, 0
	s_add_u32 s44, s44, s20
	s_addc_u32 s45, s45, 0
	s_add_u32 s46, s30, 0x5500000
	s_addc_u32 s47, s31, 0
	s_add_u32 s46, s46, s25
	s_addc_u32 s47, s47, 0
	v_lshlrev_b32_e32 v6, 3, v155
	v_lshlrev_b32_e32 v7, 4, v155
	v_add_u32_e32 v129, 0x1000, v7
	v_mov_b32_e32 v8, 0
	v_mov_b32_e32 v9, 0
	v_mov_b32_e32 v10, 0
	v_mov_b32_e32 v11, 0
	v_mov_b32_e32 v12, 0
	v_mov_b32_e32 v13, 0
	v_mov_b32_e32 v14, 0
	v_mov_b32_e32 v15, 0
	v_mov_b32_e32 v16, 0
	v_mov_b32_e32 v17, 0
	v_mov_b32_e32 v18, 0
	v_mov_b32_e32 v19, 0
	v_mov_b32_e32 v20, 0
	v_mov_b32_e32 v21, 0
	v_mov_b32_e32 v22, 0
	v_mov_b32_e32 v23, 0
	s_mov_b32 s39, 0
	s_add_i32 s37, s39, 0
	s_min_u32 s37, s37, 0x7f
	s_lshl_b32 s38, s37, 13
	s_add_u32 s82, s44, s38
	s_addc_u32 s83, s45, 0
	global_load_dwordx2 v[24:25], v6, s[82:83]
	global_load_dwordx2 v[26:27], v6, s[82:83] offset:512
	global_load_dwordx2 v[28:29], v6, s[82:83] offset:1024
	global_load_dwordx2 v[30:31], v6, s[82:83] offset:1536
	s_add_u32 s82, s46, s38
	s_addc_u32 s83, s47, 0
	global_load_dwordx4 v[56:59], v7, s[82:83]
	global_load_dwordx4 v[60:63], v7, s[82:83] offset:1024
	global_load_dwordx4 v[64:67], v7, s[82:83] offset:2048
	global_load_dwordx4 v[68:71], v7, s[82:83] offset:3072
	global_load_dwordx4 v[72:75], v129, s[82:83]
	global_load_dwordx4 v[76:79], v129, s[82:83] offset:1024
	global_load_dwordx4 v[80:83], v129, s[82:83] offset:2048
	global_load_dwordx4 v[84:87], v129, s[82:83] offset:3072
	s_add_i32 s37, s39, 1
	s_min_u32 s37, s37, 0x7f
	s_lshl_b32 s38, s37, 13
	s_add_u32 s82, s44, s38
	s_addc_u32 s83, s45, 0
	global_load_dwordx2 v[32:33], v6, s[82:83]
	global_load_dwordx2 v[34:35], v6, s[82:83] offset:512
	global_load_dwordx2 v[36:37], v6, s[82:83] offset:1024
	global_load_dwordx2 v[38:39], v6, s[82:83] offset:1536
	s_add_u32 s82, s46, s38
	s_addc_u32 s83, s47, 0
	global_load_dwordx4 v[88:91], v7, s[82:83]
	global_load_dwordx4 v[92:95], v7, s[82:83] offset:1024
	global_load_dwordx4 v[96:99], v7, s[82:83] offset:2048
	global_load_dwordx4 v[100:103], v7, s[82:83] offset:3072
	global_load_dwordx4 v[104:107], v129, s[82:83]
	global_load_dwordx4 v[108:111], v129, s[82:83] offset:1024
	global_load_dwordx4 v[112:115], v129, s[82:83] offset:2048
	global_load_dwordx4 v[116:119], v129, s[82:83] offset:3072
	s_add_i32 s37, s39, 2
	s_min_u32 s37, s37, 0x7f
	s_lshl_b32 s38, s37, 13
	s_add_u32 s82, s44, s38
	s_addc_u32 s83, s45, 0
	global_load_dwordx2 v[40:41], v6, s[82:83]
	global_load_dwordx2 v[42:43], v6, s[82:83] offset:512
	global_load_dwordx2 v[44:45], v6, s[82:83] offset:1024
	global_load_dwordx2 v[46:47], v6, s[82:83] offset:1536
	s_add_u32 s82, s46, s38
	s_addc_u32 s83, s47, 0
	global_load_dwordx4 v[132:135], v7, s[82:83]
	global_load_dwordx4 v[136:139], v7, s[82:83] offset:1024
	global_load_dwordx4 v[140:143], v7, s[82:83] offset:2048
	global_load_dwordx4 v[144:147], v7, s[82:83] offset:3072
	global_load_dwordx4 v[148:151], v129, s[82:83]
	global_load_dwordx4 v[164:167], v129, s[82:83] offset:1024
	global_load_dwordx4 v[168:171], v129, s[82:83] offset:2048
	global_load_dwordx4 v[172:175], v129, s[82:83] offset:3072
	s_waitcnt vmcnt(0)
.Lsg_loop:
	s_add_i32 s37, s39, 3
	s_min_u32 s37, s37, 0x7f
	s_lshl_b32 s38, s37, 13
	s_add_u32 s82, s44, s38
	s_addc_u32 s83, s45, 0
	global_load_dwordx2 v[48:49], v6, s[82:83]
	global_load_dwordx2 v[50:51], v6, s[82:83] offset:512
	global_load_dwordx2 v[52:53], v6, s[82:83] offset:1024
	global_load_dwordx2 v[54:55], v6, s[82:83] offset:1536
	s_add_u32 s82, s46, s38
	s_addc_u32 s83, s47, 0
	global_load_dwordx4 v[176:179], v7, s[82:83]
	global_load_dwordx4 v[184:187], v7, s[82:83] offset:1024
	global_load_dwordx4 v[188:191], v7, s[82:83] offset:2048
	global_load_dwordx4 v[192:195], v7, s[82:83] offset:3072
	global_load_dwordx4 v[196:199], v129, s[82:83]
	global_load_dwordx4 v[200:203], v129, s[82:83] offset:1024
	global_load_dwordx4 v[204:207], v129, s[82:83] offset:2048
	global_load_dwordx4 v[208:211], v129, s[82:83] offset:3072
	s_waitcnt vmcnt(48)
	v_cvt_pk_bf16_f32 v120, v8, v9
	v_cvt_pk_bf16_f32 v121, v10, v11
	v_cvt_pk_bf16_f32 v122, v12, v13
	v_cvt_pk_bf16_f32 v123, v14, v15
	v_cvt_pk_bf16_f32 v124, v16, v17
	v_cvt_pk_bf16_f32 v125, v18, v19
	v_cvt_pk_bf16_f32 v126, v20, v21
	v_cvt_pk_bf16_f32 v127, v22, v23
	s_add_i32 s37, s39, 0
	s_lshl_b32 s38, s37, 13
	s_add_u32 s40, s44, s38
	s_addc_u32 s41, s45, 0
	global_store_dwordx2 v6, v[120:121], s[40:41]
	global_store_dwordx2 v6, v[122:123], s[40:41] offset:512
	global_store_dwordx2 v6, v[124:125], s[40:41] offset:1024
	global_store_dwordx2 v6, v[126:127], s[40:41] offset:1536
	v_lshlrev_b32_e32 v8, 16, v24
	v_and_b32_e32 v9, 0xffff0000, v24
	v_lshlrev_b32_e32 v10, 16, v25
	v_and_b32_e32 v11, 0xffff0000, v25
	v_lshlrev_b32_e32 v12, 16, v26
	v_and_b32_e32 v13, 0xffff0000, v26
	v_lshlrev_b32_e32 v14, 16, v27
	v_and_b32_e32 v15, 0xffff0000, v27
	v_lshlrev_b32_e32 v16, 16, v28
	v_and_b32_e32 v17, 0xffff0000, v28
	v_lshlrev_b32_e32 v18, 16, v29
	v_and_b32_e32 v19, 0xffff0000, v29
	v_lshlrev_b32_e32 v20, 16, v30
	v_and_b32_e32 v21, 0xffff0000, v30
	v_lshlrev_b32_e32 v22, 16, v31
	v_and_b32_e32 v23, 0xffff0000, v31
	s_nop 1
	v_mfma_f32_16x16x32_bf16 v[8:11], v[56:59], v[120:123], v[8:11]
	v_mfma_f32_16x16x32_bf16 v[12:15], v[64:67], v[120:123], v[12:15]
	v_mfma_f32_16x16x32_bf16 v[16:19], v[72:75], v[120:123], v[16:19]
	v_mfma_f32_16x16x32_bf16 v[20:23], v[80:83], v[120:123], v[20:23]
	v_mfma_f32_16x16x32_bf16 v[8:11], v[60:63], v[124:127], v[8:11]
	v_mfma_f32_16x16x32_bf16 v[12:15], v[68:71], v[124:127], v[12:15]
	v_mfma_f32_16x16x32_bf16 v[16:19], v[76:79], v[124:127], v[16:19]
	v_mfma_f32_16x16x32_bf16 v[20:23], v[84:87], v[124:127], v[20:23]
	s_add_i32 s37, s39, 4
	s_min_u32 s37, s37, 0x7f
	s_lshl_b32 s38, s37, 13
	s_add_u32 s82, s44, s38
	s_addc_u32 s83, s45, 0
	global_load_dwordx2 v[24:25], v6, s[82:83]
	global_load_dwordx2 v[26:27], v6, s[82:83] offset:512
	global_load_dwordx2 v[28:29], v6, s[82:83] offset:1024
	global_load_dwordx2 v[30:31], v6, s[82:83] offset:1536
	s_add_u32 s82, s46, s38
	s_addc_u32 s83, s47, 0
	global_load_dwordx4 v[56:59], v7, s[82:83]
	global_load_dwordx4 v[60:63], v7, s[82:83] offset:1024
	global_load_dwordx4 v[64:67], v7, s[82:83] offset:2048
	global_load_dwordx4 v[68:71], v7, s[82:83] offset:3072
	global_load_dwordx4 v[72:75], v129, s[82:83]
	global_load_dwordx4 v[76:79], v129, s[82:83] offset:1024
	global_load_dwordx4 v[80:83], v129, s[82:83] offset:2048
	global_load_dwordx4 v[84:87], v129, s[82:83] offset:3072
	s_waitcnt vmcnt(48)
; __device__ __forceinline__ float bf_lo(unsigned u) { return __uint_as_float(u << 16); }
; __device__ __forceinline__ float bf_hi(unsigned u) { return __uint_as_float(u & 0xffff0000u); }
; __device__ __forceinline__ unsigned pk2(float lo, float hi) { return pg8::cvt_pk_bf16(lo, hi); }
; __device__ __forceinline__ void scan_phase(const Ctx& X, int wave, int lane) {
;     ...
;         for (int c0 = 0; c0 < NCH; c0 += 4) {
; #pragma unroll
;             for (int k = 0; k < 4; ++k) {
;                 const int c = c0 + k;
;                 SCAN_LOAD_G((k + 3) & 3, c + 3)
;                 bf16_t* bcc = bc0 + (size_t)c * 4096;
;                 u32x2 sp[4];
; #pragma unroll
;                 for (int t = 0; t < 4; ++t) { sp[t].x = pk2(S[t][0], S[t][1]); sp[t].y = pk2(S[t][2], S[t][3]);
;                     asm volatile("" : "+v"(sp[t].x) : "v"(cb[k][t].x));
;                     *(u32x2*)(bcc + 256 * t) = sp[t]; }
;                 bf16x8 bfr[2];
; #pragma unroll
;                 for (int s2 = 0; s2 < 2; ++s2) { u32x4 w; w.x = sp[2 * s2].x; w.y = sp[2 * s2].y; w.z = sp[2 * s2 + 1].x; w.w = sp[2 * s2 + 1].y; bfr[s2] = __builtin_bit_cast(bf16x8, w); }
; #pragma unroll
;                 for (int t = 0; t < 4; ++t) {
;                     f32x4 acc = (f32x4){bf_lo(cb[k][t].x), bf_hi(cb[k][t].x), bf_lo(cb[k][t].y), bf_hi(cb[k][t].y)};
; #pragma unroll
;                     for (int s2 = 0; s2 < 2; ++s2) { u32x4 w; w.x = ca[k][t][s2][0].x; w.y = ca[k][t][s2][0].y; w.z = ca[k][t][s2][1].x; w.w = ca[k][t][s2][1].y;
;                         acc = __builtin_amdgcn_mfma_f32_16x16x32_bf16(__builtin_bit_cast(bf16x8, w), bfr[s2], acc, 0, 0, 0); }
;                     S[t][0] = acc[0]; S[t][1] = acc[1]; S[t][2] = acc[2]; S[t][3] = acc[3];
;                 }
;             }
	v_cvt_pk_bf16_f32 v120, v8, v9
	v_cvt_pk_bf16_f32 v121, v10, v11
	v_cvt_pk_bf16_f32 v122, v12, v13
	v_cvt_pk_bf16_f32 v123, v14, v15
	v_cvt_pk_bf16_f32 v124, v16, v17
	v_cvt_pk_bf16_f32 v125, v18, v19
	v_cvt_pk_bf16_f32 v126, v20, v21
	v_cvt_pk_bf16_f32 v127, v22, v23
	s_add_i32 s37, s39, 1
	s_lshl_b32 s38, s37, 13
	s_add_u32 s40, s44, s38
	s_addc_u32 s41, s45, 0
	global_store_dwordx2 v6, v[120:121], s[40:41]
	global_store_dwordx2 v6, v[122:123], s[40:41] offset:512
	global_store_dwordx2 v6, v[124:125], s[40:41] offset:1024
	global_store_dwordx2 v6, v[126:127], s[40:41] offset:1536
	v_lshlrev_b32_e32 v8, 16, v32
	v_and_b32_e32 v9, 0xffff0000, v32
	v_lshlrev_b32_e32 v10, 16, v33
	v_and_b32_e32 v11, 0xffff0000, v33
	v_lshlrev_b32_e32 v12, 16, v34
	v_and_b32_e32 v13, 0xffff0000, v34
	v_lshlrev_b32_e32 v14, 16, v35
	v_and_b32_e32 v15, 0xffff0000, v35
	v_lshlrev_b32_e32 v16, 16, v36
	v_and_b32_e32 v17, 0xffff0000, v36
	v_lshlrev_b32_e32 v18, 16, v37
	v_and_b32_e32 v19, 0xffff0000, v37
	v_lshlrev_b32_e32 v20, 16, v38
	v_and_b32_e32 v21, 0xffff0000, v38
	v_lshlrev_b32_e32 v22, 16, v39
	v_and_b32_e32 v23, 0xffff0000, v39
	s_nop 1
	v_mfma_f32_16x16x32_bf16 v[8:11], v[88:91], v[120:123], v[8:11]
	v_mfma_f32_16x16x32_bf16 v[12:15], v[96:99], v[120:123], v[12:15]
	v_mfma_f32_16x16x32_bf16 v[16:19], v[104:107], v[120:123], v[16:19]
	v_mfma_f32_16x16x32_bf16 v[20:23], v[112:115], v[120:123], v[20:23]
	v_mfma_f32_16x16x32_bf16 v[8:11], v[92:95], v[124:127], v[8:11]
	v_mfma_f32_16x16x32_bf16 v[12:15], v[100:103], v[124:127], v[12:15]
	v_mfma_f32_16x16x32_bf16 v[16:19], v[108:111], v[124:127], v[16:19]
	v_mfma_f32_16x16x32_bf16 v[20:23], v[116:119], v[124:127], v[20:23]
	s_add_i32 s37, s39, 5
	s_min_u32 s37, s37, 0x7f
	s_lshl_b32 s38, s37, 13
	s_add_u32 s82, s44, s38
	s_addc_u32 s83, s45, 0
	global_load_dwordx2 v[32:33], v6, s[82:83]
	global_load_dwordx2 v[34:35], v6, s[82:83] offset:512
	global_load_dwordx2 v[36:37], v6, s[82:83] offset:1024
	global_load_dwordx2 v[38:39], v6, s[82:83] offset:1536
	s_add_u32 s82, s46, s38
	s_addc_u32 s83, s47, 0
	global_load_dwordx4 v[88:91], v7, s[82:83]
	global_load_dwordx4 v[92:95], v7, s[82:83] offset:1024
	global_load_dwordx4 v[96:99], v7, s[82:83] offset:2048
	global_load_dwordx4 v[100:103], v7, s[82:83] offset:3072
	global_load_dwordx4 v[104:107], v129, s[82:83]
	global_load_dwordx4 v[108:111], v129, s[82:83] offset:1024
	global_load_dwordx4 v[112:115], v129, s[82:83] offset:2048
	global_load_dwordx4 v[116:119], v129, s[82:83] offset:3072
	s_waitcnt vmcnt(48)
	v_cvt_pk_bf16_f32 v120, v8, v9
	v_cvt_pk_bf16_f32 v121, v10, v11
	v_cvt_pk_bf16_f32 v122, v12, v13
	v_cvt_pk_bf16_f32 v123, v14, v15
	v_cvt_pk_bf16_f32 v124, v16, v17
	v_cvt_pk_bf16_f32 v125, v18, v19
	v_cvt_pk_bf16_f32 v126, v20, v21
	v_cvt_pk_bf16_f32 v127, v22, v23
	s_add_i32 s37, s39, 2
	s_lshl_b32 s38, s37, 13
	s_add_u32 s40, s44, s38
	s_addc_u32 s41, s45, 0
	global_store_dwordx2 v6, v[120:121], s[40:41]
	global_store_dwordx2 v6, v[122:123], s[40:41] offset:512
	global_store_dwordx2 v6, v[124:125], s[40:41] offset:1024
	global_store_dwordx2 v6, v[126:127], s[40:41] offset:1536
	v_lshlrev_b32_e32 v8, 16, v40
	v_and_b32_e32 v9, 0xffff0000, v40
	v_lshlrev_b32_e32 v10, 16, v41
	v_and_b32_e32 v11, 0xffff0000, v41
	v_lshlrev_b32_e32 v12, 16, v42
	v_and_b32_e32 v13, 0xffff0000, v42
	v_lshlrev_b32_e32 v14, 16, v43
	v_and_b32_e32 v15, 0xffff0000, v43
	v_lshlrev_b32_e32 v16, 16, v44
	v_and_b32_e32 v17, 0xffff0000, v44
	v_lshlrev_b32_e32 v18, 16, v45
	v_and_b32_e32 v19, 0xffff0000, v45
	v_lshlrev_b32_e32 v20, 16, v46
	v_and_b32_e32 v21, 0xffff0000, v46
	v_lshlrev_b32_e32 v22, 16, v47
	v_and_b32_e32 v23, 0xffff0000, v47
	s_nop 1
	v_mfma_f32_16x16x32_bf16 v[8:11], v[132:135], v[120:123], v[8:11]
	v_mfma_f32_16x16x32_bf16 v[12:15], v[140:143], v[120:123], v[12:15]
	v_mfma_f32_16x16x32_bf16 v[16:19], v[148:151], v[120:123], v[16:19]
	v_mfma_f32_16x16x32_bf16 v[20:23], v[168:171], v[120:123], v[20:23]
	v_mfma_f32_16x16x32_bf16 v[8:11], v[136:139], v[124:127], v[8:11]
	v_mfma_f32_16x16x32_bf16 v[12:15], v[144:147], v[124:127], v[12:15]
	v_mfma_f32_16x16x32_bf16 v[16:19], v[164:167], v[124:127], v[16:19]
	v_mfma_f32_16x16x32_bf16 v[20:23], v[172:175], v[124:127], v[20:23]
	s_add_i32 s37, s39, 6
	s_min_u32 s37, s37, 0x7f
	s_lshl_b32 s38, s37, 13
	s_add_u32 s82, s44, s38
	s_addc_u32 s83, s45, 0
	global_load_dwordx2 v[40:41], v6, s[82:83]
	global_load_dwordx2 v[42:43], v6, s[82:83] offset:512
	global_load_dwordx2 v[44:45], v6, s[82:83] offset:1024
	global_load_dwordx2 v[46:47], v6, s[82:83] offset:1536
	s_add_u32 s82, s46, s38
	s_addc_u32 s83, s47, 0
	global_load_dwordx4 v[132:135], v7, s[82:83]
	global_load_dwordx4 v[136:139], v7, s[82:83] offset:1024
	global_load_dwordx4 v[140:143], v7, s[82:83] offset:2048
	global_load_dwordx4 v[144:147], v7, s[82:83] offset:3072
	global_load_dwordx4 v[148:151], v129, s[82:83]
	global_load_dwordx4 v[164:167], v129, s[82:83] offset:1024
	global_load_dwordx4 v[168:171], v129, s[82:83] offset:2048
	global_load_dwordx4 v[172:175], v129, s[82:83] offset:3072
	s_waitcnt vmcnt(48)
	v_cvt_pk_bf16_f32 v120, v8, v9
	v_cvt_pk_bf16_f32 v121, v10, v11
	v_cvt_pk_bf16_f32 v122, v12, v13
	v_cvt_pk_bf16_f32 v123, v14, v15
	v_cvt_pk_bf16_f32 v124, v16, v17
	v_cvt_pk_bf16_f32 v125, v18, v19
	v_cvt_pk_bf16_f32 v126, v20, v21
	v_cvt_pk_bf16_f32 v127, v22, v23
	s_add_i32 s37, s39, 3
	s_lshl_b32 s38, s37, 13
	s_add_u32 s40, s44, s38
	s_addc_u32 s41, s45, 0
	global_store_dwordx2 v6, v[120:121], s[40:41]
	global_store_dwordx2 v6, v[122:123], s[40:41] offset:512
	global_store_dwordx2 v6, v[124:125], s[40:41] offset:1024
	global_store_dwordx2 v6, v[126:127], s[40:41] offset:1536
	v_lshlrev_b32_e32 v8, 16, v48
	v_and_b32_e32 v9, 0xffff0000, v48
	v_lshlrev_b32_e32 v10, 16, v49
	v_and_b32_e32 v11, 0xffff0000, v49
	v_lshlrev_b32_e32 v12, 16, v50
	v_and_b32_e32 v13, 0xffff0000, v50
	v_lshlrev_b32_e32 v14, 16, v51
	v_and_b32_e32 v15, 0xffff0000, v51
	v_lshlrev_b32_e32 v16, 16, v52
	v_and_b32_e32 v17, 0xffff0000, v52
	v_lshlrev_b32_e32 v18, 16, v53
	v_and_b32_e32 v19, 0xffff0000, v53
	v_lshlrev_b32_e32 v20, 16, v54
	v_and_b32_e32 v21, 0xffff0000, v54
	v_lshlrev_b32_e32 v22, 16, v55
	v_and_b32_e32 v23, 0xffff0000, v55
	s_nop 1
	v_mfma_f32_16x16x32_bf16 v[8:11], v[176:179], v[120:123], v[8:11]
	v_mfma_f32_16x16x32_bf16 v[12:15], v[188:191], v[120:123], v[12:15]
	v_mfma_f32_16x16x32_bf16 v[16:19], v[196:199], v[120:123], v[16:19]
	v_mfma_f32_16x16x32_bf16 v[20:23], v[204:207], v[120:123], v[20:23]
	v_mfma_f32_16x16x32_bf16 v[8:11], v[184:187], v[124:127], v[8:11]
	v_mfma_f32_16x16x32_bf16 v[12:15], v[192:195], v[124:127], v[12:15]
	v_mfma_f32_16x16x32_bf16 v[16:19], v[200:203], v[124:127], v[16:19]
	v_mfma_f32_16x16x32_bf16 v[20:23], v[208:211], v[124:127], v[20:23]
	s_add_i32 s39, s39, 4
	s_cmpk_lt_u32 s39, 0x80
	s_cbranch_scc1 .Lsg_loop
	s_branch .LBB0_739

; #define LAS __attribute__((address_space(3)))
; template <class Tp> __device__ __forceinline__ LAS Tp* opq(LAS Tp* p) { asm volatile("" : "+v"(p)); return p; }
; __device__ __forceinline__ int unit_id(int mixer, int b, int h, int c) { return ((mixer * 4 + b) * 4 + h) * NCH + c; }
; __device__ __forceinline__ void mixer_out_phase(const Ctx& X, LAS unsigned char* lds, int layer, int tid, int wave, int lane) {
;     constexpr int GP = 264;
;     const bf16_t* proj = WSP(const bf16_t, WS_PROJ);
;     bf16_t* mix = WSP(bf16_t, WS_MIX);
;     for (int u = blockIdx.x; u < 1536; u += gridDim.x) {
;         asm volatile("" : "+v"(lane), "+v"(tid));
;         LAS bf16_t* GT = opq((LAS bf16_t*)lds);
;         const int r = lane & 15, q = lane >> 4, h = wave >> 1, half = wave & 1;
;         const int mixer = u >> 9, rem = u & 511, b = rem >> 7, c = rem & 127;
;         const int uid = unit_id(mixer, b, h, c);
;         const int goff = mixer == 0 ? C_RG : (mixer == 1 ? C_GG : C_HG), moff = mixer == 0 ? 0 : (mixer == 1 ? 512 : 768);
;         const size_t row0 = (size_t)b * T + c * 64;
;         u32x4 gv[4];
.Lgs2_done:
	s_waitcnt vmcnt(0)
	s_branch .Lgs2_pad
	s_nop 0
	s_nop 0
	s_nop 0
	s_nop 0
	s_nop 0
	s_nop 0
	s_nop 0
	s_nop 0
	s_nop 0
	s_nop 0
	s_nop 0
	s_nop 0
	s_nop 0
	s_nop 0
	s_nop 0
	s_nop 0
	s_nop 0
	s_nop 0
	s_nop 0
	s_nop 0
	s_nop 0
	s_nop 0
	s_nop 0
	s_nop 0
	s_nop 0
	s_nop 0
	s_nop 0
	s_nop 0
	s_nop 0
	s_nop 0
	s_nop 0
	s_nop 0
	s_nop 0
	s_nop 0
	s_nop 0
	s_nop 0
	s_nop 0
	s_nop 0
	s_nop 0
	s_nop 0
	s_nop 0
	s_nop 0
	s_nop 0
	s_nop 0
	s_nop 0
	s_nop 0
	s_nop 0
	s_nop 0
	s_nop 0
	s_nop 0
	s_nop 0
	s_nop 0
	s_nop 0
	s_nop 0
	s_nop 0
	s_nop 0
	s_nop 0
	s_nop 0
	s_nop 0
	s_nop 0
	s_nop 0
	s_nop 0
	s_nop 0
	s_nop 0
	s_nop 0
	s_nop 0
	s_nop 0
	s_nop 0
	s_nop 0
	s_nop 0
	s_nop 0
	s_nop 0
	s_nop 0
	s_nop 0
	s_nop 0
	s_nop 0
	s_nop 0
	s_nop 0
	s_nop 0
	s_nop 0
	s_nop 0
	s_nop 0
	s_nop 0
	s_nop 0
	s_nop 0
	s_nop 0
	s_nop 0
	s_nop 0
	s_nop 0
	s_nop 0
	s_nop 0
	s_nop 0
	s_nop 0
	s_nop 0
	s_nop 0
	s_nop 0
	s_nop 0
	s_nop 0
	s_nop 0
	s_nop 0
	s_nop 0
	s_nop 0
	s_nop 0
	s_nop 0
	s_nop 0
	s_nop 0
	s_nop 0
	s_nop 0
	s_nop 0
	s_nop 0
	s_nop 0
	s_nop 0
	s_nop 0
	s_nop 0
	s_nop 0
	s_nop 0
	s_nop 0
	s_nop 0
	s_nop 0
	s_nop 0
	s_nop 0
	s_nop 0
	s_nop 0
	s_nop 0
	s_nop 0
	s_nop 0
	s_nop 0
	s_nop 0
	s_nop 0
	s_nop 0
	s_nop 0
	s_nop 0
	s_nop 0
	s_nop 0
	s_nop 0
	s_nop 0
	s_nop 0
	s_nop 0
	s_nop 0
	s_nop 0
	s_nop 0
	s_nop 0
	s_nop 0
	s_nop 0
	s_nop 0
	s_nop 0
	s_nop 0
	s_nop 0
	s_nop 0
	s_nop 0
	s_nop 0
	s_nop 0
	s_nop 0
	s_nop 0
	s_nop 0
	s_nop 0
	s_nop 0
	s_nop 0
	s_nop 0
	s_nop 0
	s_nop 0
	s_nop 0
	s_nop 0
	s_nop 0
	s_nop 0
	s_nop 0
	s_nop 0
	s_nop 0
	s_nop 0
	s_nop 0
	s_nop 0
	s_nop 0
	s_nop 0
	s_nop 0
	s_nop 0
	s_nop 0
	s_nop 0
	s_nop 0
	s_nop 0
.Lgs2_pad:
.LBB0_886:
	s_or_b64 exec, exec, s[0:1]
	v_readlane_b32 s0, v253, 56
	v_readlane_b32 s1, v253, 57
	s_andn2_b64 vcc, exec, s[0:1]
	s_waitcnt lgkmcnt(0)
	s_barrier
	s_cbranch_vccnz .LBB0_890
	v_readlane_b32 s0, v254, 61
	v_readlane_b32 s1, v254, 62
	s_lshl_b32 s16, s0, 6
	s_lshl_b32 s0, s0, 8
	s_mov_b32 s1, s17
	s_lshl_b64 s[0:1], s[0:1], 2
	v_readlane_b32 s4, v253, 61
	s_add_u32 s8, s4, s0
	v_readlane_b32 s0, v253, 62
	v_readlane_b32 s44, v253, 38
	s_addc_u32 s9, s0, s1
	s_lshl_b64 s[4:5], s[16:17], 2
	v_mov_b32_e32 v104, v224
	v_mov_b32_e32 v105, v232
	s_mov_b32 s10, s2
	v_readlane_b32 s50, v253, 44
	v_readlane_b32 s51, v253, 45
	v_readlane_b32 s54, v253, 48
	v_readlane_b32 s55, v253, 49
	v_readlane_b32 s19, v253, 1
	v_readlane_b32 s20, v253, 2
	v_readlane_b32 s21, v253, 58
	v_readlane_b32 s22, v253, 59
	v_readlane_b32 s23, v253, 60
	v_readlane_b32 s45, v253, 39
	v_readlane_b32 s46, v253, 40
	v_readlane_b32 s47, v253, 41
	v_readlane_b32 s48, v253, 42
	v_readlane_b32 s49, v253, 43
	v_readlane_b32 s52, v253, 46
	v_readlane_b32 s53, v253, 47
	v_readlane_b32 s56, v253, 50
	v_readlane_b32 s57, v253, 51
	v_readlane_b32 s58, v253, 52
	v_readlane_b32 s59, v253, 53
